# attention M-phase: counted lgkmcnt waits, V reads and LDS-DMA issue interleaved with QK MFMAs
# speedup vs baseline: 1.0179x; 1.0179x over previous
; #define PBAR_M(t) do { if ((t) + 3 < NT) { WAIT_BAR(6); } else { WAIT_BAR(0); } } while (0)
; template <int VAR> __device__ __forceinline__ void block(const bf16* Q, const bf16* KVB, const bf16* KR, const float* cosT, bf16* OB, LAS unsigned char* lds, int b, int h, int qb, int t0, int wv, ...
;     ...
; #pragma unroll 1
;     for (int t = 1; t < NT; ++t) {
;         PBAR_M(t);
.LBB0_1408:
	s_cmp_lt_u32 s85, s66
	s_cselect_b64 s[6:7], -1, 0
	s_cmp_ge_u32 s85, s66
	s_cselect_b64 s[4:5], -1, 0
	s_mov_b64 s[8:9], -1
	s_cbranch_scc1 .Lat_mbar0
	s_waitcnt vmcnt(6) lgkmcnt(0)
	s_barrier
	s_branch .Lat_mreads

; #define SBAR() __builtin_amdgcn_sched_barrier(0)
; #define DMA_K(t, slot) do { if constexpr ((VAR & 16) != 0) break; __builtin_amdgcn_global_load_lds((const unsigned*)(ksrc + (size_t)TT(t) * 64 * KVW), (LAS unsigned*)(kdst + (slot) * KSLOT), 16, 0, 0); \
;                             __builtin_amdgcn_global_load_lds((const unsigned*)(rsrc + (size_t)TT(t) * 64 * ROPE), (LAS unsigned*)(rdst + (slot) * KSLOT), 16, 0, 0); } while (0)
; #define DMA_V(t, slot) do { if constexpr ((VAR & 16) == 0) __builtin_amdgcn_global_load_lds((const unsigned*)(vsrc + (size_t)TT(t) * 64 * KVW), (LAS unsigned*)(vdst + (slot) * VSLOT), 16, 0, 0); } while (0)
; #define KLOAD(slot) do { const LAS unsigned char* kb_ = kb0 + (slot) * KSLOT; _Pragma("unroll") for (int d0 = 0; d0 < 6; ++d0) { kf[2 * d0] = *(const LAS bf16x8*)(kb_ + d0 * 512); kf[2 * d0 + 1] = *(const LAS bf16x8*)(kb_ + d0 * 512 + 6144); } } while (0)
; #define VREAD(slot) do { const int vb_ = vb0 + (slot) * VSLOT; \
;         TRRD(vl[0], 0); TRRD(vh[0], 512); TRRD(vl[1], 1024); TRRD(vh[1], 1536); TRRD(vl[2], 2048); TRRD(vh[2], 2560); TRRD(vl[3], 3072); TRRD(vh[3], 3584); \
;         TRRD(vl[4], 4096); TRRD(vh[4], 4608); TRRD(vl[5], 5120); TRRD(vh[5], 5632); TRRD(vl[6], 6144); TRRD(vh[6], 6656); TRRD(vl[7], 7168); TRRD(vh[7], 7680); } while (0)
; template <int VAR> __device__ __forceinline__ void block(const bf16* Q, const bf16* KVB, const bf16* KR, const float* cosT, bf16* OB, LAS unsigned char* lds, int b, int h, int qb, int t0, int wv, ...
;     ...
;     s16x4 vl[8], vh[8];
;     ...
;         { if (t + 3 < NT) DMA_K(t + 3, (sk + 3) & 3); if (t + 2 < NT) DMA_V(t + 2, (sk + 2) & 3); }
;         SBAR();
;         KLOAD(sk); VREAD(sv);
;         SBAR();
;         QK(px0, px1);
;         SBAR(); asm volatile("s_waitcnt lgkmcnt(0)" ::: "memory"); SBAR();
;         PVALL();
.Lat_mreads:
	s_mul_i32 s98, s82, 0x3000
	v_add_u32_e32 v52, s98, v149
	v_lshl_add_u32 v255, s68, 13, v172
	ds_read_b128 v[48:51], v52
	ds_read_b128 v[174:177], v52 offset:512
	ds_read_b128 v[178:181], v52 offset:6144
	ds_read_b128 v[182:185], v52 offset:6656
	ds_read_b128 v[186:189], v52 offset:1024
	ds_read_b128 v[194:197], v52 offset:7168
	ds_read_b128 v[190:193], v52 offset:1536
	ds_read_b128 v[198:201], v52 offset:7680
	ds_read_b128 v[202:205], v52 offset:2048
	ds_read_b128 v[210:213], v52 offset:8192
	ds_read_b128 v[206:209], v52 offset:2560
	ds_read_b128 v[214:217], v52 offset:8704
	ds_read_b64_tr_b16 v[220:221], v255 offset:0x0
	ds_read_b64_tr_b16 v[222:223], v255 offset:0x200
	ds_read_b64_tr_b16 v[226:227], v255 offset:0x400
	s_waitcnt lgkmcnt(14)
	v_mfma_f32_32x32x16_bf16 v[64:79], v[48:51], v[112:115], v[32:47]
	v_mov_b64_e32 v[62:63], v[46:47]
	v_mov_b64_e32 v[60:61], v[44:45]
	v_mov_b64_e32 v[58:59], v[42:43]
	v_mov_b64_e32 v[56:57], v[40:41]
	v_mov_b64_e32 v[54:55], v[38:39]
	v_mov_b64_e32 v[52:53], v[36:37]
	v_mov_b64_e32 v[50:51], v[34:35]
	v_mov_b64_e32 v[48:49], v[32:33]
	ds_read_b64_tr_b16 v[228:229], v255 offset:0x600
	s_waitcnt lgkmcnt(14)
	v_mfma_f32_32x32x16_bf16 v[64:79], v[174:177], v[104:107], v[64:79]
	ds_read_b64_tr_b16 v[230:231], v255 offset:0x800
	s_waitcnt lgkmcnt(14)
	v_mfma_f32_32x32x16_bf16 v[48:63], v[178:181], v[112:115], v[48:63]
	ds_read_b64_tr_b16 v[232:233], v255 offset:0xa00
	s_waitcnt lgkmcnt(14)
	v_mfma_f32_32x32x16_bf16 v[48:63], v[182:185], v[104:107], v[48:63]
	s_cmp_lt_u32 s85, s66
	s_cbranch_scc0 .Lat_nodmak
	s_add_i32 s98, s82, -1
	s_and_b32 s98, s98, 3
	s_mulk_i32 s98, 0x3000
	s_add_i32 m0, s1, s98
	s_add_i32 s98, s0, s98
	global_load_lds_dwordx4 v[158:159], off
	s_add_i32 m0, s98, 0x800
	s_nop 0
	global_load_lds_dwordx4 v[156:157], off
.Lat_nodmak:
	ds_read_b64_tr_b16 v[234:235], v255 offset:0xc00
	s_waitcnt lgkmcnt(14)
	v_mfma_f32_32x32x16_bf16 v[64:79], v[186:189], v[116:119], v[64:79]
	ds_read_b64_tr_b16 v[236:237], v255 offset:0xe00
	s_waitcnt lgkmcnt(14)
	v_mfma_f32_32x32x16_bf16 v[48:63], v[194:197], v[116:119], v[48:63]
	s_add_i32 s98, s85, -1
	s_cmp_lt_u32 s98, s66
	s_cbranch_scc0 .Lat_nodmav
	s_lshl_b32 s98, s82, 13
	s_xor_b32 s98, s98, 0x4000
	s_add_i32 s98, s96, s98
	s_add_i32 m0, s98, 0xc000
	s_nop 0
	global_load_lds_dwordx4 v[154:155], off
.Lat_nodmav:
	ds_read_b64_tr_b16 v[238:239], v255 offset:0x1000
	s_waitcnt lgkmcnt(14)
	v_mfma_f32_32x32x16_bf16 v[64:79], v[190:193], v[108:111], v[64:79]
	ds_read_b64_tr_b16 v[240:241], v255 offset:0x1200
	s_waitcnt lgkmcnt(14)
	v_mfma_f32_32x32x16_bf16 v[48:63], v[198:201], v[108:111], v[48:63]
	ds_read_b64_tr_b16 v[242:243], v255 offset:0x1400
	s_waitcnt lgkmcnt(14)
	v_mfma_f32_32x32x16_bf16 v[64:79], v[202:205], v[120:123], v[64:79]
	ds_read_b64_tr_b16 v[244:245], v255 offset:0x1600
	s_waitcnt lgkmcnt(14)
	v_mfma_f32_32x32x16_bf16 v[48:63], v[210:213], v[120:123], v[48:63]
	ds_read_b64_tr_b16 v[246:247], v255 offset:0x1800
	s_waitcnt lgkmcnt(14)
	v_mfma_f32_32x32x16_bf16 v[64:79], v[206:209], v[124:127], v[64:79]
	ds_read_b64_tr_b16 v[248:249], v255 offset:0x1a00
	s_waitcnt lgkmcnt(14)
	v_mfma_f32_32x32x16_bf16 v[48:63], v[214:217], v[124:127], v[48:63]
	ds_read_b64_tr_b16 v[250:251], v255 offset:0x1c00
	ds_read_b64_tr_b16 v[252:253], v255 offset:0x1e00
	s_waitcnt lgkmcnt(14)
	v_mfma_f32_32x32x16_bf16 v[16:31], v[140:143], v[220:223], v[16:31]
	s_mov_b64 s[6:7], -1
	s_and_b64 vcc, exec, s[4:5]
	s_waitcnt lgkmcnt(12)
	v_mfma_f32_32x32x16_bf16 v[16:31], v[136:139], v[226:229], v[16:31]
	s_waitcnt lgkmcnt(10)
	v_mfma_f32_32x32x16_bf16 v[16:31], v[132:135], v[230:233], v[16:31]
	s_waitcnt lgkmcnt(8)
	v_mfma_f32_32x32x16_bf16 v[16:31], v[128:131], v[234:237], v[16:31]
	s_waitcnt lgkmcnt(6)
	v_mfma_f32_32x32x16_bf16 v[0:15], v[140:143], v[238:241], v[0:15]
	s_waitcnt lgkmcnt(4)
	v_mfma_f32_32x32x16_bf16 v[0:15], v[136:139], v[242:245], v[0:15]
	s_waitcnt lgkmcnt(2)
	v_mfma_f32_32x32x16_bf16 v[0:15], v[132:135], v[246:249], v[0:15]
	s_waitcnt lgkmcnt(0)
	v_mfma_f32_32x32x16_bf16 v[0:15], v[128:131], v[250:253], v[0:15]
	s_cbranch_vccnz .LBB0_1427
	s_andn2_b64 vcc, exec, s[6:7]
	s_cbranch_vccz .LBB0_1428

; #define LAS __attribute__((address_space(3)))
; __global__ void __launch_bounds__(NWAVES * 64, 2) hybrid_fwd(Args args) {
;     extern __shared__ __attribute__((aligned(16))) unsigned char lds_raw[];
;     LAS unsigned char* lds = (LAS unsigned char*)lds_raw;
;     const int wv0 = __builtin_amdgcn_readfirstlane(threadIdx.x >> 6);
	.amdhsa_kernel _Z10hybrid_fwd4Args
		.amdhsa_group_segment_fixed_size 0
		.amdhsa_private_segment_fixed_size 0
		.amdhsa_kernarg_size 616
		.amdhsa_user_sgpr_count 2
		.amdhsa_user_sgpr_dispatch_ptr 0
		.amdhsa_user_sgpr_queue_ptr 0
		.amdhsa_user_sgpr_kernarg_segment_ptr 1
		.amdhsa_user_sgpr_dispatch_id 0
		.amdhsa_user_sgpr_kernarg_preload_length 0
		.amdhsa_user_sgpr_kernarg_preload_offset 0
		.amdhsa_user_sgpr_private_segment_size 0
		.amdhsa_uses_dynamic_stack 0
		.amdhsa_enable_private_segment 0
		.amdhsa_system_sgpr_workgroup_id_x 1
		.amdhsa_system_sgpr_workgroup_id_y 0
		.amdhsa_system_sgpr_workgroup_id_z 0
		.amdhsa_system_sgpr_workgroup_info 0
		.amdhsa_system_vgpr_workitem_id 0
		.amdhsa_next_free_vgpr 256
		.amdhsa_next_free_sgpr 99
		.amdhsa_accum_offset 256
		.amdhsa_reserve_vcc 1
		.amdhsa_float_round_mode_32 0
		.amdhsa_float_round_mode_16_64 0
		.amdhsa_float_denorm_mode_32 3
		.amdhsa_float_denorm_mode_16_64 3
		.amdhsa_dx10_clamp 1
		.amdhsa_ieee_mode 1
		.amdhsa_fp16_overflow 0
		.amdhsa_tg_split 0
		.amdhsa_exception_fp_ieee_invalid_op 0
		.amdhsa_exception_fp_denorm_src 0
		.amdhsa_exception_fp_ieee_div_zero 0
		.amdhsa_exception_fp_ieee_overflow 0
		.amdhsa_exception_fp_ieee_underflow 0
		.amdhsa_exception_fp_ieee_inexact 0
		.amdhsa_exception_int_div_zero 0
	.end_amdhsa_kernel

; #define LAS __attribute__((address_space(3)))
; __global__ void __launch_bounds__(NWAVES * 64, 2) hybrid_fwd(Args args) {
;     extern __shared__ __attribute__((aligned(16))) unsigned char lds_raw[];
;     LAS unsigned char* lds = (LAS unsigned char*)lds_raw;
;     const int wv0 = __builtin_amdgcn_readfirstlane(threadIdx.x >> 6);
amdhsa.kernels:
  - .agpr_count:     0
    .args:
      - .offset:         0
        .size:           360
        .value_kind:     by_value
      - .offset:         360
        .size:           4
        .value_kind:     hidden_block_count_x
      - .offset:         364
        .size:           4
        .value_kind:     hidden_block_count_y
      - .offset:         368
        .size:           4
        .value_kind:     hidden_block_count_z
      - .offset:         372
        .size:           2
        .value_kind:     hidden_group_size_x
      - .offset:         374
        .size:           2
        .value_kind:     hidden_group_size_y
      - .offset:         376
        .size:           2
        .value_kind:     hidden_group_size_z
      - .offset:         378
        .size:           2
        .value_kind:     hidden_remainder_x
      - .offset:         380
        .size:           2
        .value_kind:     hidden_remainder_y
      - .offset:         382
        .size:           2
        .value_kind:     hidden_remainder_z
      - .offset:         400
        .size:           8
        .value_kind:     hidden_global_offset_x
      - .offset:         408
        .size:           8
        .value_kind:     hidden_global_offset_y
      - .offset:         416
        .size:           8
        .value_kind:     hidden_global_offset_z
      - .offset:         424
        .size:           2
        .value_kind:     hidden_grid_dims
      - .offset:         480
        .size:           4
        .value_kind:     hidden_dynamic_lds_size
    .group_segment_fixed_size: 0
    .kernarg_segment_align: 8
    .kernarg_segment_size: 616
    .language:       OpenCL C
    .language_version:
      - 2
      - 0
    .max_flat_workgroup_size: 512
    .name:           _Z10hybrid_fwd4Args
    .private_segment_fixed_size: 0
    .sgpr_count:     105
    .sgpr_spill_count: 64
    .symbol:         _Z10hybrid_fwd4Args.kd
    .uniform_work_group_size: 1
    .uses_dynamic_stack: false
    .vgpr_count:     256
    .vgpr_spill_count: 0
    .wavefront_size: 64
